# v066 plus tile-decode division fast path for power-of-two group height and first-K-tile LDS reads hoisted above the tile decode (tile-boundary trimming)
# speedup vs baseline: 1.0086x; 1.0080x over previous
.LBB0_488:
	v_add_u32_e32 v156, 0x10000, v141
	v_add_u32_e32 v172, 0x14000, v141
	ds_read_b128 v[144:147], v156
	ds_read_b128 v[148:151], v156 offset:1024
	ds_read_b128 v[152:155], v156 offset:2048
	ds_read_b128 v[156:159], v156 offset:3072
	ds_read_b128 v[160:163], v172
	ds_read_b128 v[164:167], v172 offset:1024
	ds_read_b128 v[168:171], v172 offset:2048
	ds_read_b128 v[172:175], v172 offset:3072
	ds_read_b128 v[176:179], v143
	ds_read_b128 v[180:183], v143 offset:1024
	ds_read_b128 v[184:187], v143 offset:2048
	ds_read_b128 v[188:191], v143 offset:3072
	ds_read_b128 v[192:195], v143 offset:4096
	ds_read_b128 v[196:199], v143 offset:5120
	ds_read_b128 v[200:203], v143 offset:6144
	ds_read_b128 v[204:207], v143 offset:7168
	s_add_i32 s48, s48, 1
	s_mul_i32 s9, s48, s47
	s_mul_hi_u32 s11, s48, s23
	s_add_i32 s11, s11, s9
	s_mul_i32 s9, s48, s23
	s_add_u32 s12, s9, s24
	s_addc_u32 s13, s11, s38
	v_mov_b64_e32 v[2:3], 0x660
	v_cmp_lt_i64_e64 s[34:35], s[12:13], v[2:3]
	v_mov_b64_e32 v[2:3], 0x65f
	v_cmp_gt_i64_e32 vcc, s[12:13], v[2:3]
	s_cbranch_vccnz .LBB0_490
	s_ashr_i32 s8, s12, 31
	s_lshr_b32 s8, s8, 29
	s_add_i32 s8, s12, s8
	s_ashr_i32 s9, s8, 3
	s_and_b32 s8, s8, -8
	s_sub_i32 s8, s12, s8
	s_cmp_lt_i32 s8, 0
	s_movk_i32 s10, 0xcd
	s_cselect_b32 s10, s10, 0xcc
	s_mul_i32 s8, s8, s10
	s_add_i32 s8, s8, s9
	s_mul_hi_i32 s9, s8, 0x2aaaaaab
	s_lshr_b32 s10, s9, 31
	s_ashr_i32 s9, s9, 5
	s_add_i32 s9, s9, s10
	s_lshl_b32 s10, s9, 3
	s_sub_i32 s11, 0x44, s10
	s_min_i32 s11, s11, 8
	s_mulk_i32 s9, 0xc0
	s_sub_i32 s9, s8, s9
	s_bcnt1_i32_b32 s12, s11
	s_cmp_eq_u32 s12, 1
	s_cbranch_scc0 .Lmy_divgen_0
	s_ff1_i32_b32 s12, s11
	s_lshr_b32 s8, s9, s12
	s_branch .Lmy_divjoin_0
.Lmy_divgen_0:
	s_abs_i32 s12, s11
	v_cvt_f32_u32_e32 v2, s12
	s_sub_i32 s14, 0, s12
	v_rcp_iflag_f32_e32 v2, v2
	s_abs_i32 s8, s9
	s_xor_b32 s13, s9, s11
	s_ashr_i32 s13, s13, 31
	v_mul_f32_e32 v2, 0x4f7ffffe, v2
	v_cvt_u32_f32_e32 v2, v2
	s_nop 0
	v_readfirstlane_b32 s15, v2
	s_mul_i32 s14, s14, s15
	s_mul_hi_u32 s14, s15, s14
	s_add_i32 s15, s15, s14
	s_mul_hi_u32 s14, s8, s15
	s_mul_i32 s15, s14, s12
	s_sub_i32 s8, s8, s15
	s_add_i32 s20, s14, 1
	s_sub_i32 s15, s8, s12
	s_cmp_ge_u32 s8, s12
	s_cselect_b32 s14, s20, s14
	s_cselect_b32 s8, s15, s8
	s_add_i32 s15, s14, 1
	s_cmp_ge_u32 s8, s12
	s_cselect_b32 s8, s15, s14
	s_xor_b32 s8, s8, s13
	s_sub_i32 s8, s8, s13
.Lmy_divjoin_0:
	s_mul_i32 s11, s8, s11
	s_sub_i32 s9, s9, s11
	s_add_i32 s10, s10, s9

.LBB0_1562:
	v_add_u32_e32 v158, 0x10000, v160
	ds_read_b128 v[164:167], v158
	ds_read_b128 v[168:171], v158 offset:1024
	ds_read_b128 v[172:175], v158 offset:2048
	ds_read_b128 v[176:179], v158 offset:3072
	v_add_u32_e32 v158, 0x14000, v160
	ds_read_b128 v[180:183], v158
	ds_read_b128 v[184:187], v158 offset:1024
	ds_read_b128 v[188:191], v158 offset:2048
	ds_read_b128 v[192:195], v158 offset:3072
	ds_read_b128 v[196:199], v162
	ds_read_b128 v[200:203], v162 offset:1024
	ds_read_b128 v[204:207], v162 offset:2048
	ds_read_b128 v[220:223], v162 offset:3072
	ds_read_b128 v[224:227], v162 offset:4096
	ds_read_b128 v[228:231], v162 offset:5120
	ds_read_b128 v[232:235], v162 offset:6144
	ds_read_b128 v[236:239], v162 offset:7168
	s_add_i32 s49, s49, 1
	s_mul_i32 s7, s49, s48
	s_mul_hi_u32 s9, s49, s25
	s_add_i32 s9, s9, s7
	s_mul_i32 s7, s49, s25
	s_add_u32 s10, s7, s36
	s_addc_u32 s11, s9, s42
	v_mov_b64_e32 v[2:3], s[68:69]
	v_cmp_ge_i64_e32 vcc, s[10:11], v[2:3]
	v_cmp_lt_i64_e64 s[34:35], s[10:11], v[2:3]
	s_cbranch_vccnz .LBB0_1564
	s_ashr_i32 s6, s10, 31
	s_lshr_b32 s6, s6, 29
	s_add_i32 s6, s10, s6
	s_ashr_i32 s7, s6, 3
	s_and_b32 s6, s6, -8
	s_sub_i32 s6, s10, s6
	s_cmp_lt_i32 s6, 0
	s_cselect_b32 s8, s40, s39
	s_mul_i32 s6, s8, s6
	s_add_i32 s6, s6, s7
	s_mul_hi_i32 s7, s6, 0x2e8ba2e9
	s_lshr_b32 s8, s7, 31
	s_ashr_i32 s7, s7, 6
	s_add_i32 s7, s7, s8
	s_lshl_b32 s8, s7, 3
	s_sub_i32 s9, s24, s8
	s_min_i32 s9, s9, 8
	s_mulk_i32 s7, 0x160
	s_sub_i32 s7, s6, s7
	s_bcnt1_i32_b32 s10, s9
	s_cmp_eq_u32 s10, 1
	s_cbranch_scc0 .Lmy_divgen_4
	s_ff1_i32_b32 s10, s9
	s_lshr_b32 s6, s7, s10
	s_branch .Lmy_divjoin_4
.Lmy_divgen_4:
	s_abs_i32 s10, s9
	v_cvt_f32_u32_e32 v2, s10
	s_sub_i32 s12, 0, s10
	v_rcp_iflag_f32_e32 v2, v2
	s_abs_i32 s6, s7
	s_xor_b32 s11, s7, s9
	s_ashr_i32 s11, s11, 31
	v_mul_f32_e32 v2, 0x4f7ffffe, v2
	v_cvt_u32_f32_e32 v2, v2
	s_nop 0
	v_readfirstlane_b32 s13, v2
	s_mul_i32 s12, s12, s13
	s_mul_hi_u32 s12, s13, s12
	s_add_i32 s13, s13, s12
	s_mul_hi_u32 s12, s6, s13
	s_mul_i32 s13, s12, s10
	s_sub_i32 s6, s6, s13
	s_add_i32 s15, s12, 1
	s_sub_i32 s13, s6, s10
	s_cmp_ge_u32 s6, s10
	s_cselect_b32 s12, s15, s12
	s_cselect_b32 s6, s13, s6
	s_add_i32 s13, s12, 1
	s_cmp_ge_u32 s6, s10
	s_cselect_b32 s6, s13, s12
	s_xor_b32 s6, s6, s11
	s_sub_i32 s6, s6, s11
.Lmy_divjoin_4:
	s_mul_i32 s9, s6, s9
	s_sub_i32 s7, s7, s9
	s_add_i32 s8, s7, s8
